# same as the P0 gain-hoist version, with hipcc's 2-slot pad between v_add_co (vcc) and v_addc_co kept as s_nop 0 where the first in-loop gain load used to sit
# baseline (speedup 1.0000x reference)
; __device__ __forceinline__ unsigned pk2(float lo, float hi) { return pg8::cvt_pk_bf16(lo, hi); }
; __device__ __forceinline__ void rms_row_2048(const float* xrow, const float* g, bf16* orow, int lane) {
;     const f32x4* xr = (const f32x4*)xrow + lane; const f32x4* gr = (const f32x4*)g + lane;
;     f32x4 v[8]; float s = 0.f;
; #pragma unroll
;     for (int j = 0; j < 8; ++j) { v[j] = __builtin_nontemporal_load(xr + 64 * j); s += (v[j].x * v[j].x + v[j].y * v[j].y) + (v[j].z * v[j].z + v[j].w * v[j].w); }
;     const float r = rsqrtf(wave_sum(s) * (1.f / 2048.f) + EPS);
;     v2u* o8 = (v2u*)orow + lane;
; #pragma unroll
;     for (int j = 0; j < 8; ++j) { const f32x4 gg = gr[64 * j]; v2u o; o.x = pk2(v[j].x * r * gg.x, v[j].y * r * gg.y); o.y = pk2(v[j].z * r * gg.z, v[j].w * r * gg.w); o8[64 * j] = o; }
; }
.LBB0_23:
	global_load_dwordx4 v[26:29], v[16:17], off offset:-3072 nt
	global_load_dwordx4 v[30:33], v[16:17], off offset:-2048 nt
	global_load_dwordx4 v[2:5], v[16:17], off nt
	global_load_dwordx4 v[34:37], v[16:17], off offset:-1024 nt
	s_waitcnt vmcnt(19)
	v_add_co_u32_e32 v50, vcc, 0xfffff000, v16
	s_nop 0
	s_nop 0
	v_addc_co_u32_e32 v51, vcc, -1, v17, vcc
	global_load_dwordx4 v[42:45], v[50:51], off offset:-3072 nt
	global_load_dwordx4 v[46:49], v[50:51], off offset:-2048 nt
	s_nop 0
	global_load_dwordx4 v[50:53], v[50:51], off offset:-1024 nt
	s_nop 0
	global_load_dwordx4 v[54:57], v[16:17], off offset:-4096 nt
	s_add_i32 s3, s3, s12
	s_cmpk_gt_i32 s3, 0x1fff
	v_lshl_add_u64 v[16:17], v[16:17], 0, s[0:1]
	s_waitcnt vmcnt(7)
	v_mul_f32_e32 v81, v26, v26
	s_waitcnt vmcnt(6)
	v_pk_mul_f32 v[58:59], v[32:33], v[32:33]
	v_pk_mul_f32 v[60:61], v[30:31], v[30:31]
	s_waitcnt vmcnt(4)
	v_mul_f32_e32 v62, v35, v35
	v_mul_f32_e32 v64, v37, v37
	v_mul_f32_e32 v79, v4, v4
	v_mul_f32_e32 v87, v5, v5
	v_pk_mov_b32 v[66:67], v[60:61], v[58:59] op_sel:[1,0]
	v_mov_b32_e32 v61, v59
	v_pk_fma_f32 v[58:59], v[34:35], v[34:35], v[62:63] op_sel_hi:[1,1,0]
	v_pk_fma_f32 v[62:63], v[36:37], v[36:37], v[64:65] op_sel_hi:[1,1,0]
	s_waitcnt vmcnt(3)
	v_mov_b32_e32 v68, v43
	s_waitcnt vmcnt(2)
	v_mov_b32_e32 v69, v47
	v_mov_b32_e32 v72, v45
	v_mov_b32_e32 v73, v49
	v_mov_b32_e32 v64, v42
	v_mov_b32_e32 v65, v46
	v_mov_b32_e32 v70, v44
	v_mov_b32_e32 v71, v48
	s_waitcnt vmcnt(1)
	v_pk_mul_f32 v[74:75], v[52:53], v[52:53]
	v_pk_mul_f32 v[76:77], v[50:51], v[50:51]
	v_pk_add_f32 v[60:61], v[66:67], v[60:61]
	v_mov_b32_e32 v59, v79
	v_mov_b32_e32 v63, v87
	v_pk_mul_f32 v[66:67], v[68:69], v[68:69]
	v_pk_mul_f32 v[68:69], v[72:73], v[72:73]
	v_pk_mov_b32 v[72:73], v[76:77], v[74:75] op_sel:[1,0]
	v_mov_b32_e32 v77, v75
	v_pk_add_f32 v[58:59], v[58:59], v[62:63]
	v_pk_fma_f32 v[62:63], v[64:65], v[64:65], v[66:67]
	v_pk_fma_f32 v[64:65], v[70:71], v[70:71], v[68:69]
	s_waitcnt vmcnt(0)
	v_mul_f32_e32 v78, v55, v55
	v_mul_f32_e32 v80, v57, v57
	v_pk_add_f32 v[66:67], v[72:73], v[76:77]
	v_pk_add_f32 v[62:63], v[62:63], v[64:65]
	v_mul_f32_e32 v82, v27, v27
	v_mul_f32_e32 v83, v28, v28
	v_mul_f32_e32 v84, v29, v29
	v_pk_fma_f32 v[74:75], v[54:55], v[54:55], v[78:79] op_sel_hi:[1,1,0]
	v_pk_fma_f32 v[78:79], v[56:57], v[56:57], v[80:81] op_sel_hi:[1,1,0]
	v_pk_add_f32 v[64:65], v[66:67], v[66:67] op_sel:[0,1] op_sel_hi:[1,0]
	v_pk_add_f32 v[62:63], v[62:63], v[62:63] op_sel:[0,1] op_sel_hi:[1,0]
	v_mov_b32_e32 v75, v83
	v_mov_b32_e32 v79, v84
	v_mov_b32_e32 v65, v82
	v_mov_b32_e32 v63, v81
	v_pk_add_f32 v[66:67], v[74:75], v[78:79]
	v_pk_add_f32 v[62:63], v[62:63], v[64:65]
	v_mul_f32_e32 v85, v2, v2
	v_pk_add_f32 v[62:63], v[62:63], v[66:67]
	v_mul_f32_e32 v86, v3, v3
	v_pk_add_f32 v[60:61], v[60:61], v[60:61] op_sel:[0,1] op_sel_hi:[1,0]
	v_pk_add_f32 v[62:63], v[62:63], v[62:63] op_sel:[0,1] op_sel_hi:[1,0]
	v_mov_b32_e32 v61, v86
	v_mov_b32_e32 v63, v85
	v_pk_add_f32 v[60:61], v[62:63], v[60:61]
	s_nop 0
	v_pk_add_f32 v[58:59], v[60:61], v[58:59]
	s_nop 0
	v_add_f32_e32 v58, v58, v59
	ds_bpermute_b32 v59, v1, v58
	s_waitcnt lgkmcnt(0)
	v_add_f32_e32 v58, v58, v59
	ds_bpermute_b32 v59, v20, v58
	s_waitcnt lgkmcnt(0)
	v_add_f32_e32 v58, v58, v59
	ds_bpermute_b32 v59, v21, v58
	s_waitcnt lgkmcnt(0)
	v_add_f32_e32 v58, v58, v59
	ds_bpermute_b32 v59, v22, v58
	s_waitcnt lgkmcnt(0)
	v_add_f32_e32 v58, v58, v59
	ds_bpermute_b32 v59, v23, v58
	s_waitcnt lgkmcnt(0)
	v_add_f32_e32 v58, v58, v59
	ds_bpermute_b32 v59, v24, v58
	s_waitcnt lgkmcnt(0)
	v_add_f32_e32 v58, v58, v59
	v_fmamk_f32 v58, v58, 0x3a000000, v25
	v_mul_f32_e32 v59, 0x4b800000, v58
	v_cmp_gt_f32_e32 vcc, s8, v58
	s_nop 1
	v_cndmask_b32_e32 v58, v58, v59, vcc
	v_rsq_f32_e32 v58, v58
	s_nop 0
	v_mul_f32_e32 v59, 0x45800000, v58
	v_cndmask_b32_e32 v58, v58, v59, vcc
	v_mul_f32_e32 v42, v42, v58
	v_mul_f32_e32 v43, v43, v58
	v_mul_f32_e32 v44, v44, v58
	v_mul_f32_e32 v45, v45, v58
	v_mul_f32_e32 v38, v176, v42
	v_mul_f32_e32 v39, v177, v43
	v_mul_f32_e32 v40, v178, v44
	v_mul_f32_e32 v41, v179, v45
	v_cvt_pk_bf16_f32 v38, v38, v39
	v_cvt_pk_bf16_f32 v39, v40, v41
	global_store_dwordx2 v[18:19], v[38:39], off offset:-2048
	v_mul_f32_e32 v42, v46, v58
	v_mul_f32_e32 v43, v47, v58
	v_mul_f32_e32 v44, v48, v58
	v_mul_f32_e32 v45, v49, v58
	v_mul_f32_e32 v26, v26, v58
	v_mul_f32_e32 v27, v27, v58
	v_mul_f32_e32 v28, v28, v58
	v_mul_f32_e32 v29, v29, v58
	v_mul_f32_e32 v30, v30, v58
	v_mul_f32_e32 v31, v31, v58
	v_mul_f32_e32 v32, v32, v58
	v_mul_f32_e32 v33, v33, v58
	v_mul_f32_e32 v2, v2, v58
	v_mul_f32_e32 v3, v3, v58
	v_mul_f32_e32 v4, v4, v58
	v_mul_f32_e32 v5, v5, v58
	v_mul_f32_e32 v38, v180, v42
	v_mul_f32_e32 v39, v181, v43
	v_mul_f32_e32 v40, v182, v44
	v_mul_f32_e32 v41, v183, v45
	v_cvt_pk_bf16_f32 v38, v38, v39
	v_cvt_pk_bf16_f32 v39, v40, v41
	global_store_dwordx2 v[18:19], v[38:39], off offset:-1536
	v_mul_f32_e32 v42, v50, v58
	v_mul_f32_e32 v43, v51, v58
	v_mul_f32_e32 v44, v52, v58
	v_mul_f32_e32 v45, v53, v58
	v_mul_f32_e32 v38, v184, v42
	v_mul_f32_e32 v39, v185, v43
	v_mul_f32_e32 v40, v186, v44
	v_mul_f32_e32 v41, v187, v45
	v_cvt_pk_bf16_f32 v38, v38, v39
	v_cvt_pk_bf16_f32 v39, v40, v41
	global_store_dwordx2 v[18:19], v[38:39], off offset:-1024
	v_mul_f32_e32 v42, v54, v58
	v_mul_f32_e32 v43, v55, v58
	v_mul_f32_e32 v44, v56, v58
	v_mul_f32_e32 v45, v57, v58
	v_mul_f32_e32 v38, v42, v188
	v_mul_f32_e32 v39, v43, v189
	v_mul_f32_e32 v40, v44, v190
	v_mul_f32_e32 v41, v45, v191
	v_cvt_pk_bf16_f32 v38, v38, v39
	v_cvt_pk_bf16_f32 v39, v40, v41
	global_store_dwordx2 v[18:19], v[38:39], off offset:-512
	v_mul_f32_e32 v26, v26, v192
	v_mul_f32_e32 v27, v27, v193
	v_mul_f32_e32 v28, v28, v194
	v_mul_f32_e32 v29, v29, v195
	v_cvt_pk_bf16_f32 v26, v26, v27
	v_cvt_pk_bf16_f32 v27, v28, v29
	global_store_dwordx2 v[18:19], v[26:27], off
	v_mul_f32_e32 v26, v30, v196
	v_mul_f32_e32 v27, v31, v197
	v_mul_f32_e32 v28, v32, v198
	v_mul_f32_e32 v29, v33, v199
	v_cvt_pk_bf16_f32 v26, v26, v27
	v_cvt_pk_bf16_f32 v27, v28, v29
	global_store_dwordx2 v[18:19], v[26:27], off offset:512
	v_mul_f32_e32 v30, v34, v58
	v_mul_f32_e32 v31, v35, v58
	v_mul_f32_e32 v32, v36, v58
	v_mul_f32_e32 v33, v37, v58
	v_mul_f32_e32 v26, v30, v200
	v_mul_f32_e32 v27, v31, v201
	v_mul_f32_e32 v28, v32, v202
	v_mul_f32_e32 v29, v33, v203
	v_cvt_pk_bf16_f32 v26, v26, v27
	v_cvt_pk_bf16_f32 v27, v28, v29
	global_store_dwordx2 v[18:19], v[26:27], off offset:1024
	v_mul_f32_e32 v2, v2, v204
	v_mul_f32_e32 v3, v3, v205
	v_mul_f32_e32 v4, v4, v206
	v_mul_f32_e32 v5, v5, v207
	v_cvt_pk_bf16_f32 v2, v2, v3
	v_cvt_pk_bf16_f32 v3, v4, v5
	global_store_dwordx2 v[18:19], v[2:3], off offset:1536
	v_lshl_add_u64 v[18:19], v[18:19], 0, s[6:7]
	s_cbranch_scc0 .LBB0_23
